# dn_prep steps 1-2: s_setprio 3 for wave 0 (it alone also runs the gate/scan step), reset after its step-2 block
# speedup vs baseline: 1.0074x; 1.0074x over previous
; DI void dn_prep_item(const Params& p, int l, int item, int next_item, u32x4 (&pre)[12], unsigned char* lds, int tid) {
;     ...
;     const int h = item & 7, n = (item >> 3) & 31, b = item >> 8, lane = tid & 63;
;     float* Qs = (float*)lds; float* Ks = Qs + 4160; float* Vs = Ks + 4160; float* Ls = Vs + 4160; float* AIs = Ls + 4096; float* XS = AIs + 4096;
;     float* Gs = XS + 64 * 129; float* BETAs = Gs + 64; float* EGs = BETAs + 64;
;     bf16_t* KH = (bf16_t*)(EGs + 64); bf16_t* KL = KH + 64 * 72; bf16_t* QH = KL + 64 * 72; bf16_t* QL = QH + 64 * 72;
;     const float* DAB = (const float*)(p.ws + OFF_DAB);
;     const float* cw = p.in[12] + (size_t)l * 4 * 1536;
;     float da_raw = 0.f, db_raw = 0.f, dtb = 0.f, alog = 0.f;
;     if (tid < 64) { const size_t tok = (size_t)b * SEQL + n * 64 + tid; da_raw = DAB[tok * 16 + h]; db_raw = DAB[tok * 16 + 8 + h]; dtb = p.in[14][l * 8 + h]; alog = p.in[13][l * 8 + h]; }
.LBB0_281:
	s_cmp_eq_u32 s71, 0
	s_cbranch_scc0 .Lw0prio
	s_setprio 3

; DI void dn_prep_item(const Params& p, int l, int item, int next_item, u32x4 (&pre)[12], unsigned char* lds, int tid) {
;     ...
;     __syncthreads();
;     {
;         const int wv = tid >> 6, c = lane & 15, g = lane >> 4;
;         for (int t = wv; t < 20; t += 8) { const int isq = t >= 10, tt = isq ? t - 10 : t, it = (tt >= 6) ? 3 : ((tt >= 3) ? 2 : ((tt >= 1) ? 1 : 0)), jt = tt - it * (it + 1) / 2;
.LBB0_315:
	s_or_b64 exec, exec, s[8:9]
	s_setprio 0
	v_ashrrev_i32_e32 v60, 6, v54
	v_lshlrev_b32_e32 v56, 1, v54
	v_and_b32_e32 v61, 15, v54
	v_lshrrev_b32_e32 v8, 4, v30
	v_cmp_gt_i32_e32 vcc, 20, v60
	s_waitcnt lgkmcnt(0)
	s_barrier
	s_and_saveexec_b64 s[12:13], vcc
	s_cbranch_execz .LBB0_350
	v_lshlrev_b32_e32 v4, 3, v8
	v_lshlrev_b32_e32 v5, 4, v8
	v_add_u32_e32 v9, v71, v5
	v_add_u32_e32 v10, v72, v5
	v_lshlrev_b32_e32 v11, 2, v8
	s_mov_b64 s[14:15], 0
	v_lshlrev_b32_e32 v12, 1, v4
	v_mov_b32_e32 v13, v60
